# pass 1: end-of-stage LDS wait counts only up to the staged key tile write; the wave-private histogram adds issued after it stay in flight across the barrier
# speedup vs baseline: 1.0086x; 1.0086x over previous
.Lp1_c1:
	ds_read_b128 v[176:179], v99 offset:8192
	ds_read_b128 v[180:183], v99 offset:12288
	ds_read_b128 v[230:233], v99 offset:9216
	ds_read_b128 v[234:237], v99 offset:13312
	ds_read_b128 v[238:241], v99 offset:10240
	ds_read_b128 v[242:245], v99 offset:14336
	ds_read_b128 v[246:249], v99 offset:11264
	ds_read_b128 v[50:53], v99 offset:15360
	v_max_i32_e32 v56, 0, v8
	v_max_i32_e32 v57, 0, v0
	v_max_i32_e32 v60, 0, v9
	v_max_i32_e32 v61, 0, v1
	v_max_i32_e32 v64, 0, v10
	v_max_i32_e32 v65, 0, v2
	v_max_i32_e32 v154, 0, v11
	v_max_i32_e32 v155, 0, v3
	v_mul_f32_e32 v156, v100, v56
	v_mul_f32_e32 v157, v101, v57
	s_waitcnt lgkmcnt(7)
	v_mfma_f32_32x32x16_bf16 v[198:213], v[34:37], v[176:179], 0
	v_fmac_f32_e32 v156, v102, v60
	v_fmac_f32_e32 v157, v103, v61
	v_fmac_f32_e32 v156, v104, v64
	v_fmac_f32_e32 v157, v105, v65
	v_fmac_f32_e32 v156, v106, v154
	v_fmac_f32_e32 v157, v107, v155
	v_max_i32_e32 v56, 0, v12
	v_max_i32_e32 v57, 0, v4
	v_max_i32_e32 v60, 0, v13
	v_max_i32_e32 v61, 0, v5
	v_max_i32_e32 v64, 0, v14
	s_waitcnt lgkmcnt(6)
	v_mfma_f32_32x32x16_bf16 v[214:229], v[34:37], v[180:183], 0
	s_waitcnt vmcnt(3)
	ds_write_b128 v140, v[20:23]
	s_add_i32 s1, s0, 5
	s_min_i32 s1, s1, s14
	v_mad_i64_i32 v[184:185], s[2:3], s1, v193, v[116:117]
	global_load_dwordx4 v[20:23], v[184:185], off
	v_max_i32_e32 v65, 0, v6
	v_max_i32_e32 v154, 0, v15
	v_max_i32_e32 v155, 0, v7
	v_fmac_f32_e32 v156, v108, v56
	v_fmac_f32_e32 v157, v109, v57
	v_fmac_f32_e32 v156, v110, v60
	v_fmac_f32_e32 v157, v111, v61
	v_fmac_f32_e32 v156, v112, v64
	v_fmac_f32_e32 v157, v113, v65
	v_fmac_f32_e32 v156, v114, v154
	v_fmac_f32_e32 v157, v115, v155
	s_waitcnt lgkmcnt(6)
	v_mfma_f32_32x32x16_bf16 v[198:213], v[38:41], v[230:233], v[198:213]
	v_bfe_u32 v56, v157, 19, 12
	v_bfe_u32 v64, v156, 19, 12
	v_med3_u32 v56, v56, s94, v194
	v_med3_u32 v64, v64, s94, v194
	v_sub_u32_e32 v57, 0x86f, v56
	v_add_u32_e32 v60, 0xfffffb90, v56
	v_sub_u32_e32 v65, 0x86f, v64
	v_add_u32_e32 v154, 0xfffffb90, v64
	v_cmp_gt_f32_e32 vcc, 0, v157
	s_nop 1
	v_cndmask_b32_e32 v56, v60, v57, vcc
	s_waitcnt lgkmcnt(5)
	v_mfma_f32_32x32x16_bf16 v[214:229], v[38:41], v[234:237], v[214:229]
	v_cmp_gt_f32_e32 vcc, 0, v156
	v_lshl_add_u32 v61, v56, 2, v33
	ds_add_u32 v61, v188
	v_cndmask_b32_e32 v64, v154, v65, vcc
	v_lshl_add_u32 v155, v64, 2, v33
	ds_add_u32 v155, v188 offset:4096
	v_max_i32_e32 v56, 0, v168
	v_max_i32_e32 v57, 0, v160
	v_max_i32_e32 v60, 0, v169
	v_max_i32_e32 v61, 0, v161
	v_max_i32_e32 v64, 0, v170
	s_waitcnt lgkmcnt(6)
	v_mfma_f32_32x32x16_bf16 v[198:213], v[42:45], v[238:241], v[198:213]
	v_max_i32_e32 v65, 0, v162
	v_max_i32_e32 v154, 0, v171
	v_max_i32_e32 v155, 0, v163
	v_mul_f32_e32 v156, v100, v56
	v_mul_f32_e32 v157, v101, v57
	v_fmac_f32_e32 v156, v102, v60
	v_fmac_f32_e32 v157, v103, v61
	v_fmac_f32_e32 v156, v104, v64
	v_fmac_f32_e32 v157, v105, v65
	v_fmac_f32_e32 v156, v106, v154
	v_fmac_f32_e32 v157, v107, v155
	s_waitcnt lgkmcnt(5)
	v_mfma_f32_32x32x16_bf16 v[214:229], v[42:45], v[242:245], v[214:229]
	v_max_i32_e32 v56, 0, v172
	v_max_i32_e32 v57, 0, v164
	v_max_i32_e32 v60, 0, v173
	v_max_i32_e32 v61, 0, v165
	v_max_i32_e32 v64, 0, v174
	v_max_i32_e32 v65, 0, v166
	v_max_i32_e32 v154, 0, v175
	v_max_i32_e32 v155, 0, v167
	v_fmac_f32_e32 v156, v108, v56
	v_fmac_f32_e32 v157, v109, v57
	v_fmac_f32_e32 v156, v110, v60
	s_waitcnt lgkmcnt(4)
	v_mfma_f32_32x32x16_bf16 v[198:213], v[46:49], v[246:249], v[198:213]
	v_fmac_f32_e32 v157, v111, v61
	v_fmac_f32_e32 v156, v112, v64
	v_fmac_f32_e32 v157, v113, v65
	v_fmac_f32_e32 v156, v114, v154
	v_fmac_f32_e32 v157, v115, v155
	v_bfe_u32 v56, v157, 19, 12
	v_bfe_u32 v64, v156, 19, 12
	v_med3_u32 v56, v56, s94, v194
	v_med3_u32 v64, v64, s94, v194
	v_sub_u32_e32 v57, 0x86f, v56
	v_add_u32_e32 v60, 0xfffffb90, v56
	s_waitcnt lgkmcnt(3)
	v_mfma_f32_32x32x16_bf16 v[214:229], v[46:49], v[50:53], v[214:229]
	v_sub_u32_e32 v65, 0x86f, v64
	v_add_u32_e32 v154, 0xfffffb90, v64
	v_cmp_gt_f32_e32 vcc, 0, v157
	s_nop 1
	v_cndmask_b32_e32 v56, v60, v57, vcc
	v_cmp_gt_f32_e32 vcc, 0, v156
	v_lshl_add_u32 v61, v56, 2, v33
	ds_add_u32 v61, v188
	v_cndmask_b32_e32 v64, v154, v65, vcc
	v_lshl_add_u32 v155, v64, 2, v33
	ds_add_u32 v155, v188 offset:4096
	s_waitcnt lgkmcnt(4)
	s_barrier
	s_add_u32 s0, s0, 1
	s_cmp_ge_u32 s0, s13
	s_cbranch_scc1 .Lp1_drain1
.Lp1_c2:
	ds_read_b128 v[176:179], v99 offset:0
	ds_read_b128 v[180:183], v99 offset:4096
	ds_read_b128 v[230:233], v99 offset:1024
	ds_read_b128 v[234:237], v99 offset:5120
	ds_read_b128 v[238:241], v99 offset:2048
	ds_read_b128 v[242:245], v99 offset:6144
	ds_read_b128 v[246:249], v99 offset:3072
	ds_read_b128 v[50:53], v99 offset:7168
	v_max_i32_e32 v56, 0, v206
	v_max_i32_e32 v57, 0, v198
	v_max_i32_e32 v60, 0, v207
	v_max_i32_e32 v61, 0, v199
	v_max_i32_e32 v64, 0, v208
	v_max_i32_e32 v65, 0, v200
	v_max_i32_e32 v154, 0, v209
	v_max_i32_e32 v155, 0, v201
	v_mul_f32_e32 v156, v100, v56
	v_mul_f32_e32 v157, v101, v57
	s_waitcnt lgkmcnt(7)
	v_mfma_f32_32x32x16_bf16 v[0:15], v[34:37], v[176:179], 0
	v_fmac_f32_e32 v156, v102, v60
	v_fmac_f32_e32 v157, v103, v61
	v_fmac_f32_e32 v156, v104, v64
	v_fmac_f32_e32 v157, v105, v65
	v_fmac_f32_e32 v156, v106, v154
	v_fmac_f32_e32 v157, v107, v155
	v_max_i32_e32 v56, 0, v210
	v_max_i32_e32 v57, 0, v202
	v_max_i32_e32 v60, 0, v211
	v_max_i32_e32 v61, 0, v203
	v_max_i32_e32 v64, 0, v212
	s_waitcnt lgkmcnt(6)
	v_mfma_f32_32x32x16_bf16 v[160:175], v[34:37], v[180:183], 0
	s_waitcnt vmcnt(3)
	ds_write_b128 v140, v[24:27] offset:8192
	s_add_i32 s1, s0, 5
	s_min_i32 s1, s1, s14
	v_mad_i64_i32 v[184:185], s[2:3], s1, v193, v[116:117]
	global_load_dwordx4 v[24:27], v[184:185], off
	v_max_i32_e32 v65, 0, v204
	v_max_i32_e32 v154, 0, v213
	v_max_i32_e32 v155, 0, v205
	v_fmac_f32_e32 v156, v108, v56
	v_fmac_f32_e32 v157, v109, v57
	v_fmac_f32_e32 v156, v110, v60
	v_fmac_f32_e32 v157, v111, v61
	v_fmac_f32_e32 v156, v112, v64
	v_fmac_f32_e32 v157, v113, v65
	v_fmac_f32_e32 v156, v114, v154
	v_fmac_f32_e32 v157, v115, v155
	s_waitcnt lgkmcnt(6)
	v_mfma_f32_32x32x16_bf16 v[0:15], v[38:41], v[230:233], v[0:15]
	v_bfe_u32 v56, v157, 19, 12
	v_bfe_u32 v64, v156, 19, 12
	v_med3_u32 v56, v56, s94, v194
	v_med3_u32 v64, v64, s94, v194
	v_sub_u32_e32 v57, 0x86f, v56
	v_add_u32_e32 v60, 0xfffffb90, v56
	v_sub_u32_e32 v65, 0x86f, v64
	v_add_u32_e32 v154, 0xfffffb90, v64
	v_cmp_gt_f32_e32 vcc, 0, v157
	s_nop 1
	v_cndmask_b32_e32 v56, v60, v57, vcc
	s_waitcnt lgkmcnt(5)
	v_mfma_f32_32x32x16_bf16 v[160:175], v[38:41], v[234:237], v[160:175]
	v_cmp_gt_f32_e32 vcc, 0, v156
	v_lshl_add_u32 v61, v56, 2, v33
	ds_add_u32 v61, v188
	v_cndmask_b32_e32 v64, v154, v65, vcc
	v_lshl_add_u32 v155, v64, 2, v33
	ds_add_u32 v155, v188 offset:4096
	v_max_i32_e32 v56, 0, v222
	v_max_i32_e32 v57, 0, v214
	v_max_i32_e32 v60, 0, v223
	v_max_i32_e32 v61, 0, v215
	v_max_i32_e32 v64, 0, v224
	s_waitcnt lgkmcnt(6)
	v_mfma_f32_32x32x16_bf16 v[0:15], v[42:45], v[238:241], v[0:15]
	v_max_i32_e32 v65, 0, v216
	v_max_i32_e32 v154, 0, v225
	v_max_i32_e32 v155, 0, v217
	v_mul_f32_e32 v156, v100, v56
	v_mul_f32_e32 v157, v101, v57
	v_fmac_f32_e32 v156, v102, v60
	v_fmac_f32_e32 v157, v103, v61
	v_fmac_f32_e32 v156, v104, v64
	v_fmac_f32_e32 v157, v105, v65
	v_fmac_f32_e32 v156, v106, v154
	v_fmac_f32_e32 v157, v107, v155
	s_waitcnt lgkmcnt(5)
	v_mfma_f32_32x32x16_bf16 v[160:175], v[42:45], v[242:245], v[160:175]
	v_max_i32_e32 v56, 0, v226
	v_max_i32_e32 v57, 0, v218
	v_max_i32_e32 v60, 0, v227
	v_max_i32_e32 v61, 0, v219
	v_max_i32_e32 v64, 0, v228
	v_max_i32_e32 v65, 0, v220
	v_max_i32_e32 v154, 0, v229
	v_max_i32_e32 v155, 0, v221
	v_fmac_f32_e32 v156, v108, v56
	v_fmac_f32_e32 v157, v109, v57
	v_fmac_f32_e32 v156, v110, v60
	s_waitcnt lgkmcnt(4)
	v_mfma_f32_32x32x16_bf16 v[0:15], v[46:49], v[246:249], v[0:15]
	v_fmac_f32_e32 v157, v111, v61
	v_fmac_f32_e32 v156, v112, v64
	v_fmac_f32_e32 v157, v113, v65
	v_fmac_f32_e32 v156, v114, v154
	v_fmac_f32_e32 v157, v115, v155
	v_bfe_u32 v56, v157, 19, 12
	v_bfe_u32 v64, v156, 19, 12
	v_med3_u32 v56, v56, s94, v194
	v_med3_u32 v64, v64, s94, v194
	v_sub_u32_e32 v57, 0x86f, v56
	v_add_u32_e32 v60, 0xfffffb90, v56
	s_waitcnt lgkmcnt(3)
	v_mfma_f32_32x32x16_bf16 v[160:175], v[46:49], v[50:53], v[160:175]
	v_sub_u32_e32 v65, 0x86f, v64
	v_add_u32_e32 v154, 0xfffffb90, v64
	v_cmp_gt_f32_e32 vcc, 0, v157
	s_nop 1
	v_cndmask_b32_e32 v56, v60, v57, vcc
	v_cmp_gt_f32_e32 vcc, 0, v156
	v_lshl_add_u32 v61, v56, 2, v33
	ds_add_u32 v61, v188
	v_cndmask_b32_e32 v64, v154, v65, vcc
	v_lshl_add_u32 v155, v64, 2, v33
	ds_add_u32 v155, v188 offset:4096
	s_waitcnt lgkmcnt(4)
	s_barrier
	s_add_u32 s0, s0, 1
	s_cmp_ge_u32 s0, s13
	s_cbranch_scc1 .Lp1_drain0
.Lp1_c3:
	ds_read_b128 v[176:179], v99 offset:8192
	ds_read_b128 v[180:183], v99 offset:12288
	ds_read_b128 v[230:233], v99 offset:9216
	ds_read_b128 v[234:237], v99 offset:13312
	ds_read_b128 v[238:241], v99 offset:10240
	ds_read_b128 v[242:245], v99 offset:14336
	ds_read_b128 v[246:249], v99 offset:11264
	ds_read_b128 v[50:53], v99 offset:15360
	v_max_i32_e32 v56, 0, v8
	v_max_i32_e32 v57, 0, v0
	v_max_i32_e32 v60, 0, v9
	v_max_i32_e32 v61, 0, v1
	v_max_i32_e32 v64, 0, v10
	v_max_i32_e32 v65, 0, v2
	v_max_i32_e32 v154, 0, v11
	v_max_i32_e32 v155, 0, v3
	v_mul_f32_e32 v156, v100, v56
	v_mul_f32_e32 v157, v101, v57
	s_waitcnt lgkmcnt(7)
	v_mfma_f32_32x32x16_bf16 v[198:213], v[34:37], v[176:179], 0
	v_fmac_f32_e32 v156, v102, v60
	v_fmac_f32_e32 v157, v103, v61
	v_fmac_f32_e32 v156, v104, v64
	v_fmac_f32_e32 v157, v105, v65
	v_fmac_f32_e32 v156, v106, v154
	v_fmac_f32_e32 v157, v107, v155
	v_max_i32_e32 v56, 0, v12
	v_max_i32_e32 v57, 0, v4
	v_max_i32_e32 v60, 0, v13
	v_max_i32_e32 v61, 0, v5
	v_max_i32_e32 v64, 0, v14
	s_waitcnt lgkmcnt(6)
	v_mfma_f32_32x32x16_bf16 v[214:229], v[34:37], v[180:183], 0
	s_waitcnt vmcnt(3)
	ds_write_b128 v140, v[28:31]
	s_add_i32 s1, s0, 5
	s_min_i32 s1, s1, s14
	v_mad_i64_i32 v[184:185], s[2:3], s1, v193, v[116:117]
	global_load_dwordx4 v[28:31], v[184:185], off
	v_max_i32_e32 v65, 0, v6
	v_max_i32_e32 v154, 0, v15
	v_max_i32_e32 v155, 0, v7
	v_fmac_f32_e32 v156, v108, v56
	v_fmac_f32_e32 v157, v109, v57
	v_fmac_f32_e32 v156, v110, v60
	v_fmac_f32_e32 v157, v111, v61
	v_fmac_f32_e32 v156, v112, v64
	v_fmac_f32_e32 v157, v113, v65
	v_fmac_f32_e32 v156, v114, v154
	v_fmac_f32_e32 v157, v115, v155
	s_waitcnt lgkmcnt(6)
	v_mfma_f32_32x32x16_bf16 v[198:213], v[38:41], v[230:233], v[198:213]
	v_bfe_u32 v56, v157, 19, 12
	v_bfe_u32 v64, v156, 19, 12
	v_med3_u32 v56, v56, s94, v194
	v_med3_u32 v64, v64, s94, v194
	v_sub_u32_e32 v57, 0x86f, v56
	v_add_u32_e32 v60, 0xfffffb90, v56
	v_sub_u32_e32 v65, 0x86f, v64
	v_add_u32_e32 v154, 0xfffffb90, v64
	v_cmp_gt_f32_e32 vcc, 0, v157
	s_nop 1
	v_cndmask_b32_e32 v56, v60, v57, vcc
	s_waitcnt lgkmcnt(5)
	v_mfma_f32_32x32x16_bf16 v[214:229], v[38:41], v[234:237], v[214:229]
	v_cmp_gt_f32_e32 vcc, 0, v156
	v_lshl_add_u32 v61, v56, 2, v33
	ds_add_u32 v61, v188
	v_cndmask_b32_e32 v64, v154, v65, vcc
	v_lshl_add_u32 v155, v64, 2, v33
	ds_add_u32 v155, v188 offset:4096
	v_max_i32_e32 v56, 0, v168
	v_max_i32_e32 v57, 0, v160
	v_max_i32_e32 v60, 0, v169
	v_max_i32_e32 v61, 0, v161
	v_max_i32_e32 v64, 0, v170
	s_waitcnt lgkmcnt(6)
	v_mfma_f32_32x32x16_bf16 v[198:213], v[42:45], v[238:241], v[198:213]
	v_max_i32_e32 v65, 0, v162
	v_max_i32_e32 v154, 0, v171
	v_max_i32_e32 v155, 0, v163
	v_mul_f32_e32 v156, v100, v56
	v_mul_f32_e32 v157, v101, v57
	v_fmac_f32_e32 v156, v102, v60
	v_fmac_f32_e32 v157, v103, v61
	v_fmac_f32_e32 v156, v104, v64
	v_fmac_f32_e32 v157, v105, v65
	v_fmac_f32_e32 v156, v106, v154
	v_fmac_f32_e32 v157, v107, v155
	s_waitcnt lgkmcnt(5)
	v_mfma_f32_32x32x16_bf16 v[214:229], v[42:45], v[242:245], v[214:229]
	v_max_i32_e32 v56, 0, v172
	v_max_i32_e32 v57, 0, v164
	v_max_i32_e32 v60, 0, v173
	v_max_i32_e32 v61, 0, v165
	v_max_i32_e32 v64, 0, v174
	v_max_i32_e32 v65, 0, v166
	v_max_i32_e32 v154, 0, v175
	v_max_i32_e32 v155, 0, v167
	v_fmac_f32_e32 v156, v108, v56
	v_fmac_f32_e32 v157, v109, v57
	v_fmac_f32_e32 v156, v110, v60
	s_waitcnt lgkmcnt(4)
	v_mfma_f32_32x32x16_bf16 v[198:213], v[46:49], v[246:249], v[198:213]
	v_fmac_f32_e32 v157, v111, v61
	v_fmac_f32_e32 v156, v112, v64
	v_fmac_f32_e32 v157, v113, v65
	v_fmac_f32_e32 v156, v114, v154
	v_fmac_f32_e32 v157, v115, v155
	v_bfe_u32 v56, v157, 19, 12
	v_bfe_u32 v64, v156, 19, 12
	v_med3_u32 v56, v56, s94, v194
	v_med3_u32 v64, v64, s94, v194
	v_sub_u32_e32 v57, 0x86f, v56
	v_add_u32_e32 v60, 0xfffffb90, v56
	s_waitcnt lgkmcnt(3)
	v_mfma_f32_32x32x16_bf16 v[214:229], v[46:49], v[50:53], v[214:229]
	v_sub_u32_e32 v65, 0x86f, v64
	v_add_u32_e32 v154, 0xfffffb90, v64
	v_cmp_gt_f32_e32 vcc, 0, v157
	s_nop 1
	v_cndmask_b32_e32 v56, v60, v57, vcc
	v_cmp_gt_f32_e32 vcc, 0, v156
	v_lshl_add_u32 v61, v56, 2, v33
	ds_add_u32 v61, v188
	v_cndmask_b32_e32 v64, v154, v65, vcc
	v_lshl_add_u32 v155, v64, 2, v33
	ds_add_u32 v155, v188 offset:4096
	s_waitcnt lgkmcnt(4)
	s_barrier
	s_add_u32 s0, s0, 1
	s_cmp_ge_u32 s0, s13
	s_cbranch_scc1 .Lp1_drain1
.Lp1_c0:
	ds_read_b128 v[176:179], v99 offset:0
	ds_read_b128 v[180:183], v99 offset:4096
	ds_read_b128 v[230:233], v99 offset:1024
	ds_read_b128 v[234:237], v99 offset:5120
	ds_read_b128 v[238:241], v99 offset:2048
	ds_read_b128 v[242:245], v99 offset:6144
	ds_read_b128 v[246:249], v99 offset:3072
	ds_read_b128 v[50:53], v99 offset:7168
	v_max_i32_e32 v56, 0, v206
	v_max_i32_e32 v57, 0, v198
	v_max_i32_e32 v60, 0, v207
	v_max_i32_e32 v61, 0, v199
	v_max_i32_e32 v64, 0, v208
	v_max_i32_e32 v65, 0, v200
	v_max_i32_e32 v154, 0, v209
	v_max_i32_e32 v155, 0, v201
	v_mul_f32_e32 v156, v100, v56
	v_mul_f32_e32 v157, v101, v57
	s_waitcnt lgkmcnt(7)
	v_mfma_f32_32x32x16_bf16 v[0:15], v[34:37], v[176:179], 0
	v_fmac_f32_e32 v156, v102, v60
	v_fmac_f32_e32 v157, v103, v61
	v_fmac_f32_e32 v156, v104, v64
	v_fmac_f32_e32 v157, v105, v65
	v_fmac_f32_e32 v156, v106, v154
	v_fmac_f32_e32 v157, v107, v155
	v_max_i32_e32 v56, 0, v210
	v_max_i32_e32 v57, 0, v202
	v_max_i32_e32 v60, 0, v211
	v_max_i32_e32 v61, 0, v203
	v_max_i32_e32 v64, 0, v212
	s_waitcnt lgkmcnt(6)
	v_mfma_f32_32x32x16_bf16 v[160:175], v[34:37], v[180:183], 0
	s_waitcnt vmcnt(3)
	ds_write_b128 v140, v[16:19] offset:8192
	s_add_i32 s1, s0, 5
	s_min_i32 s1, s1, s14
	v_mad_i64_i32 v[184:185], s[2:3], s1, v193, v[116:117]
	global_load_dwordx4 v[16:19], v[184:185], off
	v_max_i32_e32 v65, 0, v204
	v_max_i32_e32 v154, 0, v213
	v_max_i32_e32 v155, 0, v205
	v_fmac_f32_e32 v156, v108, v56
	v_fmac_f32_e32 v157, v109, v57
	v_fmac_f32_e32 v156, v110, v60
	v_fmac_f32_e32 v157, v111, v61
	v_fmac_f32_e32 v156, v112, v64
	v_fmac_f32_e32 v157, v113, v65
	v_fmac_f32_e32 v156, v114, v154
	v_fmac_f32_e32 v157, v115, v155
	s_waitcnt lgkmcnt(6)
	v_mfma_f32_32x32x16_bf16 v[0:15], v[38:41], v[230:233], v[0:15]
	v_bfe_u32 v56, v157, 19, 12
	v_bfe_u32 v64, v156, 19, 12
	v_med3_u32 v56, v56, s94, v194
	v_med3_u32 v64, v64, s94, v194
	v_sub_u32_e32 v57, 0x86f, v56
	v_add_u32_e32 v60, 0xfffffb90, v56
	v_sub_u32_e32 v65, 0x86f, v64
	v_add_u32_e32 v154, 0xfffffb90, v64
	v_cmp_gt_f32_e32 vcc, 0, v157
	s_nop 1
	v_cndmask_b32_e32 v56, v60, v57, vcc
	s_waitcnt lgkmcnt(5)
	v_mfma_f32_32x32x16_bf16 v[160:175], v[38:41], v[234:237], v[160:175]
	v_cmp_gt_f32_e32 vcc, 0, v156
	v_lshl_add_u32 v61, v56, 2, v33
	ds_add_u32 v61, v188
	v_cndmask_b32_e32 v64, v154, v65, vcc
	v_lshl_add_u32 v155, v64, 2, v33
	ds_add_u32 v155, v188 offset:4096
	v_max_i32_e32 v56, 0, v222
	v_max_i32_e32 v57, 0, v214
	v_max_i32_e32 v60, 0, v223
	v_max_i32_e32 v61, 0, v215
	v_max_i32_e32 v64, 0, v224
	s_waitcnt lgkmcnt(6)
	v_mfma_f32_32x32x16_bf16 v[0:15], v[42:45], v[238:241], v[0:15]
	v_max_i32_e32 v65, 0, v216
	v_max_i32_e32 v154, 0, v225
	v_max_i32_e32 v155, 0, v217
	v_mul_f32_e32 v156, v100, v56
	v_mul_f32_e32 v157, v101, v57
	v_fmac_f32_e32 v156, v102, v60
	v_fmac_f32_e32 v157, v103, v61
	v_fmac_f32_e32 v156, v104, v64
	v_fmac_f32_e32 v157, v105, v65
	v_fmac_f32_e32 v156, v106, v154
	v_fmac_f32_e32 v157, v107, v155
	s_waitcnt lgkmcnt(5)
	v_mfma_f32_32x32x16_bf16 v[160:175], v[42:45], v[242:245], v[160:175]
	v_max_i32_e32 v56, 0, v226
	v_max_i32_e32 v57, 0, v218
	v_max_i32_e32 v60, 0, v227
	v_max_i32_e32 v61, 0, v219
	v_max_i32_e32 v64, 0, v228
	v_max_i32_e32 v65, 0, v220
	v_max_i32_e32 v154, 0, v229
	v_max_i32_e32 v155, 0, v221
	v_fmac_f32_e32 v156, v108, v56
	v_fmac_f32_e32 v157, v109, v57
	v_fmac_f32_e32 v156, v110, v60
	s_waitcnt lgkmcnt(4)
	v_mfma_f32_32x32x16_bf16 v[0:15], v[46:49], v[246:249], v[0:15]
	v_fmac_f32_e32 v157, v111, v61
	v_fmac_f32_e32 v156, v112, v64
	v_fmac_f32_e32 v157, v113, v65
	v_fmac_f32_e32 v156, v114, v154
	v_fmac_f32_e32 v157, v115, v155
	v_bfe_u32 v56, v157, 19, 12
	v_bfe_u32 v64, v156, 19, 12
	v_med3_u32 v56, v56, s94, v194
	v_med3_u32 v64, v64, s94, v194
	v_sub_u32_e32 v57, 0x86f, v56
	v_add_u32_e32 v60, 0xfffffb90, v56
	s_waitcnt lgkmcnt(3)
	v_mfma_f32_32x32x16_bf16 v[160:175], v[46:49], v[50:53], v[160:175]
	v_sub_u32_e32 v65, 0x86f, v64
	v_add_u32_e32 v154, 0xfffffb90, v64
	v_cmp_gt_f32_e32 vcc, 0, v157
	s_nop 1
	v_cndmask_b32_e32 v56, v60, v57, vcc
	v_cmp_gt_f32_e32 vcc, 0, v156
	v_lshl_add_u32 v61, v56, 2, v33
	ds_add_u32 v61, v188
	v_cndmask_b32_e32 v64, v154, v65, vcc
	v_lshl_add_u32 v155, v64, 2, v33
	ds_add_u32 v155, v188 offset:4096
	s_waitcnt lgkmcnt(4)
	s_barrier
	s_add_u32 s0, s0, 1
	s_cmp_ge_u32 s0, s13
	s_cbranch_scc1 .Lp1_drain0
	s_branch .Lp1_c1
